# seam trims on v60: ATT preamble loads merged into one round, DA/SB prologue DMA no longer waits for the first Q loads, SB unit-boundary waits counted (sb_all)
# speedup vs baseline: 1.0026x; 1.0026x over previous
; #define LAS __attribute__((address_space(3)))
; __device__ __forceinline__ void da_phase(LAS unsigned char* lds, const GAS f16* __restrict__ kv, const GAS f16* __restrict__ qg, GAS f16* __restrict__ mixed, int vcu, int G, ...
;     ...
;     if (tid < 128) ((LAS float*)(lds + DA_SUBG))[tid] = subg[tid];
; __global__ void __launch_bounds__(NWAVES * 64, 2) hybrid_fwd(Args args) {
;     ...
;             const float sa = att::wave_sum(lq1[l * 64 + lane] * lk1[l * 64 + lane]), sb = att::wave_sum(lq2[l * 64 + lane] * lk2[l * 64 + lane]);
;             const float lam_init = 0.8f - 0.6f * __expf(-0.3f * (float)l);
;             const float lam = __expf(sa) - __expf(sb) + lam_init;
;             const float mgq = att::wave_max(fabsf(q_norm_g[l * 64 + lane])), mgk = att::wave_max(fabsf(k_norm_g[l * 64 + lane]));
;             const float mref = 8.0f * LOG2E * mgq * mgk * 1.001f - 10.0f;
.LBB0_476:
	s_mov_b64 s[88:89], s[48:49]
	v_or_b32_e32 v2, s22, v1
	v_readlane_b32 s36, v252, 9
	v_lshlrev_b64 v[4:5], 2, v[2:3]
	v_readlane_b32 s48, v252, 21
	v_readlane_b32 s49, v252, 22
	v_readlane_b32 s50, v252, 23
	v_readlane_b32 s51, v252, 24
	v_lshl_add_u64 v[6:7], s[48:49], 0, v[4:5]
	global_load_dword v2, v[6:7], off
	v_lshl_add_u64 v[6:7], s[50:51], 0, v[4:5]
	global_load_dword v6, v[6:7], off
	v_and_b32_e32 v8, 64, v213
	v_add_u32_e32 v8, 64, v8
	v_xor_b32_e32 v9, 1, v213
	v_cmp_lt_i32_e32 vcc, v9, v8
	v_readlane_b32 s44, v252, 17
	v_readlane_b32 s45, v252, 18
	v_cndmask_b32_e32 v9, v213, v9, vcc
	v_lshlrev_b32_e32 v12, 2, v9
	v_readlane_b32 s46, v252, 19
	v_readlane_b32 s47, v252, 20
	v_lshl_add_u64 v[10:11], s[44:45], 0, v[4:5]
	v_lshl_add_u64 v[14:15], s[92:93], 0, v[4:5]
	global_load_dword v246, v[14:15], off
	v_lshl_add_u64 v[14:15], s[94:95], 0, v[4:5]
	global_load_dword v247, v[14:15], off
	v_lshl_add_u64 v[14:15], s[46:47], 0, v[4:5]
	global_load_dword v248, v[14:15], off
	global_load_dword v249, v[10:11], off
	v_mov_b32_e32 v132, v0
	s_movk_i32 s1, 0x80
	v_readlane_b32 s37, v252, 10
	v_readlane_b32 s38, v252, 11
	v_readlane_b32 s39, v252, 12
	v_readlane_b32 s40, v252, 13
	v_readlane_b32 s41, v252, 14
	v_readlane_b32 s42, v252, 15
	v_readlane_b32 s43, v252, 16
	s_waitcnt vmcnt(0)
	v_mul_f32_e32 v7, v2, v6
	ds_bpermute_b32 v7, v12, v7
	s_waitcnt lgkmcnt(0)
	v_fmac_f32_e32 v7, v2, v6
	v_xor_b32_e32 v2, 2, v213
	v_cmp_lt_i32_e32 vcc, v2, v8
	v_xor_b32_e32 v6, 4, v213
	s_nop 0
	v_cndmask_b32_e32 v2, v213, v2, vcc
	v_lshlrev_b32_e32 v13, 2, v2
	ds_bpermute_b32 v2, v13, v7
	v_cmp_lt_i32_e32 vcc, v6, v8
	s_waitcnt lgkmcnt(0)
	v_add_f32_e32 v2, v7, v2
	v_cndmask_b32_e32 v6, v213, v6, vcc
	v_lshlrev_b32_e32 v14, 2, v6
	ds_bpermute_b32 v6, v14, v2
	s_waitcnt lgkmcnt(0)
	v_add_f32_e32 v2, v2, v6
	v_xor_b32_e32 v6, 8, v213
	v_cmp_lt_i32_e32 vcc, v6, v8
	s_nop 1
	v_cndmask_b32_e32 v6, v213, v6, vcc
	v_lshlrev_b32_e32 v15, 2, v6
	ds_bpermute_b32 v6, v15, v2
	s_waitcnt lgkmcnt(0)
	v_add_f32_e32 v2, v2, v6
	v_xor_b32_e32 v6, 16, v213
	v_cmp_lt_i32_e32 vcc, v6, v8
	s_nop 1
	v_cndmask_b32_e32 v6, v213, v6, vcc
	v_lshlrev_b32_e32 v16, 2, v6
	ds_bpermute_b32 v6, v16, v2
	s_waitcnt lgkmcnt(0)
	v_add_f32_e32 v2, v2, v6
	v_xor_b32_e32 v6, 32, v213
	v_cmp_lt_i32_e32 vcc, v6, v8
	v_cndmask_b32_e32 v6, v213, v6, vcc
	v_lshlrev_b32_e32 v17, 2, v6
	ds_bpermute_b32 v6, v17, v2
	s_waitcnt vmcnt(0)
	v_mul_f32_e32 v9, v246, v247
	ds_bpermute_b32 v9, v12, v9
	s_waitcnt lgkmcnt(0)
	v_and_b32_e32 v5, 0x7fffffff, v248
	ds_bpermute_b32 v5, v12, v5
	v_max_f32_e64 v4, |v248|, |v248|
	v_fmac_f32_e32 v9, v246, v247
	ds_bpermute_b32 v7, v13, v9
	s_waitcnt lgkmcnt(1)
	v_max_f32_e32 v5, v5, v5
	v_max_f32_e32 v4, v4, v5
	ds_bpermute_b32 v5, v13, v4
	s_waitcnt lgkmcnt(1)
	v_add_f32_e32 v7, v9, v7
	ds_bpermute_b32 v8, v14, v7
	s_waitcnt lgkmcnt(0)
	v_max_f32_e32 v5, v5, v5
	v_max_f32_e32 v4, v4, v5
	ds_bpermute_b32 v5, v14, v4
	s_waitcnt lgkmcnt(0)
	v_add_f32_e32 v7, v7, v8
	ds_bpermute_b32 v8, v15, v7
	s_barrier
	v_max_f32_e32 v5, v5, v5
	v_max_f32_e32 v4, v4, v5
	ds_bpermute_b32 v5, v15, v4
	s_waitcnt lgkmcnt(0)
	v_add_f32_e32 v7, v7, v8
	ds_bpermute_b32 v8, v16, v7
	s_waitcnt lgkmcnt(0)
	v_max_f32_e32 v5, v5, v5
	v_max_f32_e32 v4, v4, v5
	ds_bpermute_b32 v5, v16, v4
	v_add_f32_e32 v7, v7, v8
	ds_bpermute_b32 v8, v17, v7
	v_readfirstlane_b32 s0, v132
	v_cmp_gt_i32_e32 vcc, s1, v132
	s_waitcnt lgkmcnt(0)
	v_max_f32_e32 v5, v5, v5
	v_max_f32_e32 v4, v4, v5
	ds_bpermute_b32 v5, v17, v4
	s_waitcnt vmcnt(0)
	v_and_b32_e32 v10, 0x7fffffff, v249
	ds_bpermute_b32 v10, v12, v10
	v_max_f32_e64 v9, |v249|, |v249|
	s_waitcnt lgkmcnt(0)
	v_max_f32_e32 v10, v10, v10
	v_max_f32_e32 v9, v9, v10
	ds_bpermute_b32 v10, v13, v9
	s_waitcnt lgkmcnt(0)
	v_max_f32_e32 v10, v10, v10
	v_max_f32_e32 v9, v9, v10
	ds_bpermute_b32 v10, v14, v9
	s_waitcnt lgkmcnt(0)
	v_max_f32_e32 v10, v10, v10
	v_max_f32_e32 v9, v9, v10
	ds_bpermute_b32 v10, v15, v9
	s_waitcnt lgkmcnt(0)
	v_max_f32_e32 v10, v10, v10
	v_max_f32_e32 v9, v9, v10
	ds_bpermute_b32 v10, v16, v9
	s_waitcnt lgkmcnt(0)
	v_max_f32_e32 v10, v10, v10
	v_max_f32_e32 v9, v9, v10
	ds_bpermute_b32 v10, v17, v9
	s_and_saveexec_b64 s[4:5], vcc
	s_cbranch_execz .LBB0_478
	s_lshl_b32 s80, s76, 7
	s_lshl_b64 s[6:7], s[80:81], 2
	s_add_u32 s6, s96, s6
	s_addc_u32 s7, s97, s7
	v_ashrrev_i32_e32 v133, 31, v132
	v_lshl_add_u64 v[12:13], v[132:133], 2, s[6:7]
	global_load_dword v12, v[12:13], off
	v_lshl_add_u32 v11, v132, 2, 0
	v_add_u32_e32 v11, 0x24400, v11
	s_waitcnt vmcnt(0)
	ds_write_b32 v11, v12

; #define GAS __attribute__((address_space(1)))
; __host__ __device__ __forceinline__ size_t bl512(size_t row, int col) { return ((row >> 5) * 64 + (size_t)(col >> 3)) * 256 + (row & 31) * 8 + (col & 7); }
; __device__ __forceinline__ void da_phase(LAS unsigned char* lds, const GAS f16* __restrict__ kv, const GAS f16* __restrict__ qg, GAS f16* __restrict__ mixed, int vcu, int G, ...
;     ...
;     const GAS f16* ksrc = kv + ((size_t)U.b * SEQ) * KVW + U.h * 128 + koff; const GAS f16* vsrc = kv + ((size_t)U.b * SEQ) * KVW + U.h * 128 + voff;
;     h8 qn[4];
;     { const GAS f16* Qg = qg + bl512((size_t)U.b * SEQ + U.qt * 128, U.h * 128) + qoff;
; #pragma unroll
;       for (int d0 = 0; d0 < 4; ++d0) qn[d0] = *(const GAS h8*)(Qg + 512 * d0); }
; __global__ void __launch_bounds__(NWAVES * 64, 2) hybrid_fwd(Args args) {
;     ...
;             const float lam_init = 0.8f - 0.6f * __expf(-0.3f * (float)l);
;             const float lam = __expf(sa) - __expf(sb) + lam_init;
;             const float mgq = att::wave_max(fabsf(q_norm_g[l * 64 + lane])), mgk = att::wave_max(fabsf(k_norm_g[l * 64 + lane]));
;             const float mref = 8.0f * LOG2E * mgq * mgk * 1.001f - 10.0f;
.LBB0_488:
	v_add_f32_e32 v6, v2, v6
	v_cvt_f32_u32_e32 v2, s76
	v_add_f32_e32 v7, v7, v8
	v_readlane_b32 s4, v250, 2
	v_mul_f32_e32 v6, 0x3fb8aa3b, v6
	v_mul_f32_e32 v2, 0xbe99999a, v2
	v_mul_f32_e32 v2, 0x3fb8aa3b, v2
	v_mul_f32_e32 v7, 0x3fb8aa3b, v7
	v_readlane_b32 s5, v250, 3
	v_exp_f32_e32 v2, v2
	v_exp_f32_e32 v6, v6
	v_exp_f32_e32 v7, v7
	s_xor_b64 s[86:87], s[4:5], -1
	v_readlane_b32 s4, v250, 0
	s_waitcnt lgkmcnt(0)
	v_max_f32_e32 v8, v10, v10
	v_max_f32_e32 v5, v5, v5
	v_readlane_b32 s5, v250, 1
	s_add_u32 s33, s4, 0x6000000
	v_max_f32_e32 v8, v9, v8
	v_max_f32_e32 v4, v4, v5
	s_addc_u32 s26, s5, 0
	s_and_b64 vcc, exec, s[38:39]
	s_cbranch_vccnz .LBB0_531
	s_ashr_i32 s1, s0, 8
	s_ashr_i32 s4, s0, 6
	s_lshl_b32 s11, s1, 1
	s_add_i32 s11, s11, s4
	s_and_b32 s6, s11, 3
	s_lshl_b32 s5, s6, 13
	s_add_i32 s7, s5, 0
	s_add_i32 s7, s7, 0x1c000
	v_readlane_b32 s14, v250, 0
	v_readlane_b32 s15, v250, 1
	s_add_u32 s27, s14, 0x18000000
	s_addc_u32 s30, s15, 0
	v_bfe_u32 v14, v132, 5, 1
	s_lshl_b32 s36, s1, 6
	v_lshl_or_b32 v5, v14, 3, s36
	s_lshl_b32 s5, s4, 10
	s_lshl_b32 s22, s4, 2
	s_lshl_b32 s4, s11, 6
	v_ashrrev_i32_e32 v10, 3, v5
	s_and_b32 s80, s4, 0xc0
	v_ashrrev_i32_e32 v11, 31, v10
	v_lshl_add_u64 v[10:11], s[80:81], 0, v[10:11]
	s_add_i32 s31, s5, 0
	v_lshlrev_b64 v[10:11], 9, v[10:11]
	v_lshlrev_b32_e32 v5, 4, v132
	s_movk_i32 s4, 0x1f0
	s_lshl_b32 s21, s1, 3
	s_add_i32 s34, s31, 0xc000
	s_lshl_b32 s35, s6, 5
	v_and_or_b32 v10, v5, s4, v10
	v_readlane_b32 s4, v251, 8
	s_add_u32 s4, s8, s4
	s_addc_u32 s5, s9, 0
	v_readlane_b32 s14, v251, 49
	v_readlane_b32 s15, v251, 50
	s_add_u32 s4, s4, s14
	s_addc_u32 s5, s5, s15
	s_lshl_b32 s14, s10, 7
	s_ashr_i32 s15, s14, 31
	s_lshl_b64 s[14:15], s[14:15], 1
	v_readlane_b32 s18, v251, 9
	s_add_u32 s14, s14, s18
	s_addc_u32 s15, s15, 0
	s_and_b32 s15, s15, 0x7fffff
	s_and_b32 s14, s14, 0xffffff00
	v_readlane_b32 s18, v251, 10
	s_add_u32 s14, s14, s18
	v_readlane_b32 s18, v251, 11
	s_addc_u32 s15, s15, s18
	s_lshl_b64 s[14:15], s[14:15], 9
	s_add_u32 s14, s82, s14
	s_mov_b64 s[18:19], 0x4000000
	s_addc_u32 s15, s83, s15
	v_lshl_add_u64 v[10:11], v[10:11], 0, s[18:19]
	v_lshl_add_u64 v[12:13], s[14:15], 0, v[10:11]
	global_load_dwordx4 v[112:115], v[12:13], off offset:3072
	global_load_dwordx4 v[108:111], v[12:13], off offset:2048
	global_load_dwordx4 v[104:107], v[12:13], off offset:1024
	global_load_dwordx4 v[100:103], v[12:13], off
	v_fmamk_f32 v2, v2, 0xbf19999a, v214
	v_sub_f32_e32 v5, v6, v7
	v_add_f32_e32 v15, v2, v5
	v_mul_f32_e32 v5, 0x4138aa3b, v8
	v_mul_f32_e32 v4, v5, v4
	v_fmamk_f32 v133, v4, 0x3f8020c5, v215
	v_lshlrev_b32_e32 v4, 3, v132
	v_lshrrev_b32_e32 v7, 1, v132
	v_and_b32_e32 v5, 32, v4
	v_and_b32_e32 v6, 3, v132
	v_and_b32_e32 v7, 12, v7
	v_or3_b32 v8, v6, v5, v7
	v_or_b32_e32 v6, v7, v6
	v_or_b32_e32 v5, s21, v14
	v_bitop3_b32 v7, s21, v6, v14 bitop3:0x36
	v_lshlrev_b32_e32 v175, 4, v7
	v_bitop3_b32 v7, v5, v6, 2 bitop3:0x36
	v_lshlrev_b32_e32 v176, 4, v7
	v_bitop3_b32 v7, v5, v6, 4 bitop3:0x36
	v_lshlrev_b32_e32 v177, 4, v7
	v_bitop3_b32 v5, v5, v6, 6 bitop3:0x36
	v_bfe_u32 v6, v132, 2, 2
	v_and_b32_e32 v179, 32, v132
	v_lshlrev_b32_e32 v7, 1, v132
	v_lshlrev_b32_e32 v178, 4, v5
	v_or_b32_e32 v5, v6, v179
	v_and_b32_e32 v7, 32, v7
	v_lshl_or_b32 v5, v5, 8, v7
	v_and_b32_e32 v7, 24, v4
	v_lshlrev_b32_e32 v4, 6, v6
	v_bfe_u32 v9, v132, 4, 2
	v_or3_b32 v187, v5, v4, v7
	v_or_b32_e32 v4, s22, v9
	s_movk_i32 s14, 0x80
	v_ashrrev_i32_e32 v5, 31, v4
	v_bitop3_b32 v193, v187, s14, v216 bitop3:0x36
	s_movk_i32 s14, 0xc0
	v_lshlrev_b64 v[134:135], 11, v[4:5]
	v_bitop3_b32 v4, s22, v132, v9 bitop3:0x36
	v_bitop3_b32 v194, v187, s14, v216 bitop3:0x36
	v_lshlrev_b32_e32 v4, 3, v4
	s_movk_i32 s14, 0x78
	v_sub_f32_e32 v172, 1.0, v2
	v_and_b32_e32 v2, 63, v132
	v_and_or_b32 v136, v4, s14, v134
	v_xor_b32_e32 v4, v6, v9
	v_and_b32_e32 v16, 15, v132
	v_lshlrev_b32_e32 v6, 5, v4
	v_bfe_u32 v4, v2, 4, 1
	v_cmp_eq_u32_e32 vcc, v16, v4
	v_or_b32_e32 v5, 16, v8
	v_cvt_f32_ubyte0_e32 v5, v5
	v_cndmask_b32_e32 v4, 0, v217, vcc
	v_pack_b32_f16 v116, v4, v4
	v_cvt_f32_ubyte0_e32 v4, v8
	v_cvt_f16_f32_e32 v4, v4
	v_cvt_f16_f32_e32 v5, v5
; #define LAS __attribute__((address_space(3)))
; #define GAS __attribute__((address_space(1)))
; __host__ __device__ __forceinline__ size_t bl512(size_t row, int col) { return ((row >> 5) * 64 + (size_t)(col >> 3)) * 256 + (row & 31) * 8 + (col & 7); }
; __device__ __forceinline__ void da_phase(LAS unsigned char* lds, const GAS f16* __restrict__ kv, const GAS f16* __restrict__ qg, GAS f16* __restrict__ mixed, int vcu, int G, ...
;     ...
;     { const int kr = keyrow(l31);
; #pragma unroll
;       for (int d0 = 0; d0 < 4; ++d0) kfo[d0] = kr * 256 + (((8 * c + 2 * d0 + hi) ^ (kr & 15)) * 16); }
;     int vfo[4];
;     { const int q_ = (lane & 15) >> 2;
; #pragma unroll
;       for (int d0 = 0; d0 < 4; ++d0) vfo[d0] = DA_VRING + (32 * hi + q_) * 256 + ((d0 ^ q_) * 64) + ((lane >> 4) & 1) * 32 + (lane & 3) * 8; }
;     const int srow = 4 * w + (lane >> 4);
;     const size_t koff = (size_t)srow * KVW + K_DAK + (((lane & 15) ^ (srow & 15)) * 8);
;     const size_t voff = (size_t)srow * KVW + K_DAV + (((((lane & 15) >> 2) ^ (srow & 3)) * 4 + (lane & 3)) * 8);
;     const size_t qoff = S_DAQ * QG_SEC + bl512((size_t)(32 * rg + l31), c * 64 + 8 * hi);
;     h8 ones; { const f16 one = ((lane & 15) == ((lane >> 4) & 1)) ? (f16)1.0f : (f16)0.0f; ones = (h8){one, one, one, one, one, one, one, one}; }
;     h8 ba0, ba1; { const f16 z = (f16)0.0f, one = hi ? z : (f16)1.0f, k0 = hi ? z : (f16)(float)keyrow(l31), k1 = hi ? z : (f16)(float)(keyrow(l31) + 16);
;                    ba0 = (h8){one, one, k0, k0, z, z, z, z}; ba1 = (h8){one, one, k1, k1, z, z, z, z}; }
;     if (tid < 128) ((LAS float*)(lds + DA_SUBG))[tid] = subg[tid];
;     LAS unsigned* xch = (LAS unsigned*)(lds + DA_XCH + rg * 8192);
;     ...
;     DaUnit U, Un; int ui = vcu;
;     if (!da_decode(ui, U)) return;
;     const GAS f16* ksrc = kv + ((size_t)U.b * SEQ) * KVW + U.h * 128 + koff; const GAS f16* vsrc = kv + ((size_t)U.b * SEQ) * KVW + U.h * 128 + voff;
;     h8 qn[4];
;     { const GAS f16* Qg = qg + bl512((size_t)U.b * SEQ + U.qt * 128, U.h * 128) + qoff;
; #pragma unroll
;       for (int d0 = 0; d0 < 4; ++d0) qn[d0] = *(const GAS h8*)(Qg + 512 * d0); }
;     asm volatile("" : "+v"(qn[0]), "+v"(qn[1]), "+v"(qn[2]), "+v"(qn[3]));
;     DA_DMA(ksrc, vsrc, U.klo, 0, 0); DA_DMA(ksrc, vsrc, U.klo + 1, DA_KS, DA_KS);
;     int ik = 2 * DA_KS, iv = 2 * DA_KS, ck = 0, cv = 0;
	v_cmp_gt_u32_e64 s[40:41], 32, v2
	v_mov_b32_e32 v137, v135
	v_or3_b32 v134, v6, v7, v134
	v_cndmask_b32_e64 v4, 0, v4, s[40:41]
	v_cndmask_b32_e64 v5, 0, v5, s[40:41]
	s_ashr_i32 s21, s20, 31
	v_lshlrev_b32_e32 v174, 8, v8
	v_cndmask_b32_e64 v8, 0, v217, s[40:41]
	v_pack_b32_f16 v121, v4, v4
	v_pack_b32_f16 v125, v5, v5
	v_lshl_add_u64 v[4:5], v[136:137], 1, s[4:5]
	v_lshl_add_u64 v[6:7], v[134:135], 1, s[4:5]
	s_lshl_b64 s[4:5], s[20:21], 18
	v_pack_b32_f16 v120, v8, v8
	s_mov_b64 s[18:19], 0x800
	v_lshl_add_u64 v[8:9], v[4:5], 0, s[4:5]
	s_mov_b64 s[28:29], 0x20800
	v_lshl_add_u64 v[12:13], v[8:9], 0, s[18:19]
	s_mov_b32 s14, m0
	s_mov_b32 m0, s31
	s_nop 0
	global_load_lds_dwordx4 v[12:13], off
	s_mov_b32 m0, s14
	v_lshl_add_u64 v[8:9], v[8:9], 0, s[28:29]
	s_mov_b64 s[24:25], 0xc00
	s_add_i32 s14, s31, 0x2000
	s_mov_b32 s15, m0
	s_mov_b32 m0, s14
	s_nop 0
	global_load_lds_dwordx4 v[8:9], off
	s_mov_b32 m0, s15
	v_lshl_add_u64 v[8:9], v[6:7], 0, s[4:5]
	v_lshl_add_u64 v[12:13], v[8:9], 0, s[24:25]
	s_mov_b32 s14, m0
	s_mov_b32 m0, s34
	s_nop 0
	global_load_lds_dwordx4 v[12:13], off
	s_mov_b32 m0, s14
	s_add_i32 s14, s34, 0x2000
	s_add_u32 s4, s4, 0x40000
	s_mov_b64 s[42:43], 0x20c00
	s_addc_u32 s5, s5, 0
	v_lshl_add_u64 v[164:165], v[4:5], 0, s[18:19]
	v_lshl_add_u64 v[8:9], v[8:9], 0, s[42:43]
	s_mov_b32 s15, m0
	s_mov_b32 m0, s14
	s_nop 0
	global_load_lds_dwordx4 v[8:9], off
	s_mov_b32 m0, s15
	v_lshl_add_u64 v[4:5], v[4:5], 0, s[4:5]
	s_add_i32 s14, s31, 0x4000
	v_lshl_add_u64 v[8:9], v[4:5], 0, s[18:19]
	s_mov_b32 s18, m0
	s_mov_b32 m0, s14
	s_nop 0
	global_load_lds_dwordx4 v[8:9], off
	s_mov_b32 m0, s18
	v_lshl_add_u64 v[4:5], v[4:5], 0, s[28:29]
	s_add_i32 s14, s31, 0x6000
	s_mov_b32 s18, m0
	s_mov_b32 m0, s14
	s_nop 0
	global_load_lds_dwordx4 v[4:5], off
	s_mov_b32 m0, s18
	v_lshl_add_u64 v[4:5], v[6:7], 0, s[4:5]
	v_lshl_add_u64 v[166:167], v[6:7], 0, s[24:25]
	s_add_i32 s15, s31, 0x10000
	v_lshl_add_u64 v[6:7], v[4:5], 0, s[24:25]
	s_mov_b32 s4, m0
	s_mov_b32 m0, s15
	s_nop 0
	global_load_lds_dwordx4 v[6:7], off
	s_mov_b32 m0, s4
	s_add_i32 s4, s31, 0x12000
	s_bfe_u32 s21, s11, 0x10001
	s_cmpk_lt_u32 s0, 0x100
	v_lshl_add_u64 v[4:5], v[4:5], 0, s[42:43]
	s_mov_b32 s5, m0
	s_mov_b32 m0, s4
	s_nop 0
	global_load_lds_dwordx4 v[4:5], off
	s_mov_b32 m0, s5
	s_cselect_b64 s[44:45], -1, 0
	s_xor_b32 s4, s1, 1
	s_lshl_b32 s6, s6, 8
	v_lshlrev_b32_e32 v4, 2, v2
	s_lshl_b32 s5, s4, 12
	s_add_i32 s6, s6, 0
	v_and_b32_e32 v173, 31, v132
	v_add_u32_e32 v5, s7, v4
	s_add_i32 s7, s7, s5
	s_lshl_b32 s5, s1, 12
	s_add_i32 s6, s6, 0x24c00
	s_lshl_b32 s1, s1, 7
	v_add_u32_e32 v196, s7, v4
	s_add_i32 s1, s6, s1
	v_lshlrev_b32_e32 v4, 2, v173
	v_add_u32_e32 v197, s1, v4
	s_lshl_b32 s1, s4, 7
	s_and_b32 s0, s0, 0xffffff00
	s_add_i32 s6, s6, s1
	s_add_i32 s0, s0, 0
	v_add_u32_e32 v198, s6, v4
	s_add_i32 s0, s0, 0x24400
	v_lshlrev_b32_e32 v4, 4, v14
	v_lshlrev_b32_e32 v2, 8, v14
	v_and_or_b32 v6, v213, 64, v16
	v_xor_b32_e32 v140, 0x80000000, v133
	v_cndmask_b32_e64 v156, -1.0, 1.0, s[44:45]
	v_add_u32_e32 v201, s0, v4
	v_readlane_b32 s0, v251, 14
	v_bitop3_b32 v192, v187, 64, v216 bitop3:0x36
	v_mov_b32_e32 v117, v116
	v_mov_b32_e32 v118, v116
	v_mov_b32_e32 v119, v116
	v_mov_b32_e32 v122, v3
	v_mov_b32_e32 v123, v3
	v_mov_b32_e32 v124, v120
	v_mov_b32_e32 v126, v3
	v_mov_b32_e32 v127, v3
	s_mov_b64 s[60:61], 0x800
	s_mov_b64 s[62:63], 0xc00
	v_lshl_add_u64 v[138:139], s[82:83], 0, v[10:11]
	v_cmp_gt_u32_e64 s[42:43], 16, v173
	v_cndmask_b32_e64 v195, v15, 1.0, s[44:45]
	v_lshlrev_b32_e32 v199, 2, v6
	v_mov_b32_e32 v141, v140
	v_mov_b32_e32 v142, v140
	v_mov_b32_e32 v143, v140
	v_mov_b32_e32 v144, v140
	v_mov_b32_e32 v145, v140
	v_mov_b32_e32 v146, v140
	v_mov_b32_e32 v147, v140
	v_mov_b32_e32 v148, v140
	v_mov_b32_e32 v149, v140
	v_mov_b32_e32 v150, v140
	v_mov_b32_e32 v151, v140
	v_mov_b32_e32 v152, v140
	v_mov_b32_e32 v153, v140
	v_mov_b32_e32 v154, v140
	v_mov_b32_e32 v155, v140
	v_mov_b32_e32 v157, v156
	s_mov_b32 s57, 0x8000
	s_mov_b32 s37, 0
	v_lshlrev_b32_e32 v158, 1, v2
	v_add_u32_e32 v200, s5, v5
	s_mov_b32 s6, s0
	s_mov_b32 s0, s23
	s_mov_b32 s55, 0
	s_mov_b32 s22, 0x8000
	s_mov_b32 s56, s79
	s_branch .LBB0_491

; #define GAS __attribute__((address_space(1)))
; __host__ __device__ __forceinline__ size_t bl512(size_t row, int col) { return ((row >> 5) * 64 + (size_t)(col >> 3)) * 256 + (row & 31) * 8 + (col & 7); }
; #define SB_DMA(base_, kt_, slot) do { const GAS f16* b_ = (base_) + (size_t)(kt_) * 64 * KVW; const unsigned kd_ = (unsigned)__builtin_amdgcn_readfirstlane(kdst + (slot)), vd_ = (unsigned)__builtin_amdgcn_readfirstlane(vdst + (slot)); \
;         _Pragma("unroll") for (int i_ = 0; i_ < 4; ++i_) { glds16(b_ + koff[i_], kd_ + i_ * 1024); glds16(b_ + voff[i_], vd_ + i_ * 1024); } } while (0)
; __device__ __forceinline__ void sb_phase(LAS unsigned char* lds, const GAS f16* __restrict__ kv, const GAS f16* __restrict__ qg, GAS f16* __restrict__ mixed, int vcu, int G, unsigned long long& sw_acc) {
;     ...
;     const GAS f16* tbase = kv + ((size_t)U.b * SEQ) * KVW + U.hg * 256;
;     h8 qn[4]; u32x4 gn[4];
;     { const size_t grow = (size_t)U.b * SEQ + U.cq * 64 + 32 * rgp + l31; const int h = 4 * U.hg + hh;
;       const GAS f16* Qg = qg + S_SBQ * QG_SEC + bl512(grow, h * 64 + 8 * hi); const GAS f16* Gp = qg + S_SBG * QG_SEC + bl512(grow, h * 64);
; #pragma unroll
;       for (int d0 = 0; d0 < 4; ++d0) qn[d0] = *(const GAS h8*)(Qg + 512 * d0);
;       ld_groups_raw_bl(Gp, hi, gn); }
;     asm volatile("" : "+v"(qn[0]), "+v"(qn[1]), "+v"(qn[2]), "+v"(qn[3]));
;     SB_DMA(tbase, U.cq, islot); islot ^= SB_SLOT;
.LBB0_534:
	v_readlane_b32 s6, v250, 0
	v_readlane_b32 s7, v250, 1
	s_add_u32 s27, s6, 0x14000000
	s_addc_u32 s22, s7, 0
	s_ashr_i32 s6, s1, 8
	s_lshl_b32 s0, s6, 1
	s_add_i32 s0, s0, s4
	s_lshl_b32 s5, s4, 12
	s_and_b32 s0, s0, 3
	s_add_i32 s23, s5, 0
	s_lshl_b32 s11, s6, 5
	s_lshl_b32 s5, s0, 3
	s_lshl_b32 s7, s0, 1
	s_add_i32 s10, s23, 0x8000
	s_ashr_i32 s14, s11, 31
	v_readlane_b32 s15, v251, 15
	s_add_u32 s18, s15, s11
	v_readlane_b32 s15, v251, 16
	v_lshlrev_b32_e32 v2, 2, v4
	v_lshrrev_b32_e32 v5, 1, v4
	s_addc_u32 s19, s15, s14
	s_lshl_b32 s15, s0, 6
	v_readlane_b32 s20, v251, 13
	v_and_b32_e32 v2, 16, v2
	v_and_b32_e32 v12, 3, v4
	v_and_b32_e32 v5, 12, v5
	s_or_b32 s0, s20, s15
	v_bfe_u32 v11, v4, 5, 1
	v_or3_b32 v8, v12, v2, v5
	v_or_b32_e32 v2, s18, v4
	s_lshl_b64 s[18:19], s[18:19], 1
	s_lshr_b32 s0, s0, 3
	s_and_b32 s19, s19, 0xffffff
	s_andn2_b32 s18, s18, 63
	v_or_b32_e32 v6, s0, v11
	v_or_b32_e32 v6, s18, v6
	v_mov_b32_e32 v7, s19
	v_lshlrev_b64 v[6:7], 9, v[6:7]
	v_lshlrev_b32_e32 v2, 4, v2
	v_lshl_add_u64 v[6:7], s[82:83], 0, v[6:7]
	v_and_b32_e32 v2, 0x1f0, v2
	v_lshl_add_u64 v[6:7], v[6:7], 0, v[2:3]
	global_load_dwordx4 v[64:67], v[6:7], off offset:3072
	global_load_dwordx4 v[60:63], v[6:7], off offset:2048
	global_load_dwordx4 v[56:59], v[6:7], off offset:1024
	global_load_dwordx4 v[52:55], v[6:7], off
	v_or_b32_e32 v5, v5, v12
	v_lshlrev_b32_e32 v6, 9, v8
	v_or_b32_e32 v7, s5, v11
	v_bitop3_b32 v8, s5, v5, v11 bitop3:0x36
	v_lshl_or_b32 v117, v8, 4, v6
	v_bitop3_b32 v8, v7, v5, 2 bitop3:0x36
	v_lshl_or_b32 v135, v8, 4, v6
	v_bitop3_b32 v8, v7, v5, 4 bitop3:0x36
	v_bitop3_b32 v5, v7, v5, 6 bitop3:0x36
	s_or_b32 s18, s18, s0
	v_lshl_or_b32 v152, v8, 4, v6
	v_lshl_or_b32 v153, v5, 4, v6
	v_bfe_u32 v6, v4, 2, 2
	s_lshl_b64 s[18:19], s[18:19], 9
	v_lshlrev_b32_e32 v7, 9, v6
	v_lshlrev_b32_e32 v8, 1, v4
	v_lshlrev_b32_e32 v9, 3, v4
	s_add_u32 s18, s27, s18
	v_lshl_or_b32 v7, v11, 13, v7
	v_and_b32_e32 v8, 32, v8
	v_and_b32_e32 v9, 24, v9
	s_addc_u32 s19, s22, s19
	v_or3_b32 v13, v7, v8, v9
	v_lshl_add_u64 v[8:9], s[18:19], 0, v[2:3]
	v_lshlrev_b32_e32 v2, 9, v11
	v_lshl_add_u64 v[8:9], v[8:9], 0, v[2:3]
	global_load_dwordx4 v[68:71], v[8:9], off
	global_load_dwordx4 v[72:75], v[8:9], off offset:1024
	global_load_dwordx4 v[76:79], v[8:9], off offset:2048
	global_load_dwordx4 v[80:83], v[8:9], off offset:3072
	v_bitop3_b32 v15, s7, v6, 1 bitop3:0x36
	v_lshl_or_b32 v6, s4, 3, v11
	v_and_b32_e32 v116, 31, v4
	v_lshrrev_b32_e32 v5, 2, v4
	v_ashrrev_i32_e32 v7, 31, v6
	v_bitop3_b32 v14, s7, v5, 3 bitop3:0x78
	v_lshlrev_b64 v[118:119], 11, v[6:7]
	v_bitop3_b32 v5, v6, v116, 9 bitop3:0x6c
	v_lshl_or_b32 v120, v5, 3, v118
	v_lshlrev_b32_e32 v5, 2, v11
	v_and_b32_e32 v10, 63, v4
	v_and_b32_e32 v16, 28, v4
	v_bitop3_b32 v4, v5, v4, 28 bitop3:0x78
	v_or_b32_e32 v4, v4, v12
	v_lshlrev_b32_e32 v7, 3, v4
	v_or_b32_e32 v4, 2, v6
	v_readlane_b32 s0, v251, 8
	v_ashrrev_i32_e32 v5, 31, v4
	v_lshlrev_b32_e32 v2, 2, v4
	s_add_u32 s0, s8, s0
	v_lshlrev_b64 v[122:123], 11, v[4:5]
	v_bitop3_b32 v5, v4, v116, 11 bitop3:0x6c
	v_bitop3_b32 v2, v2, v16, 12 bitop3:0x6c
	v_or_b32_e32 v4, 4, v6
	s_addc_u32 s5, s9, 0
	s_lshl_b32 s7, s20, 1
	v_lshl_or_b32 v124, v5, 3, v122
	v_or_b32_e32 v2, v2, v12
	v_ashrrev_i32_e32 v5, 31, v4
	s_add_u32 s49, s0, s7
	v_lshl_or_b32 v122, v2, 3, v122
	v_lshlrev_b64 v[126:127], 11, v[4:5]
	v_bitop3_b32 v2, v4, v116, 13 bitop3:0x6c
	v_or_b32_e32 v4, 6, v6
	s_addc_u32 s0, s5, 0
	v_readlane_b32 s18, v251, 19
	v_ashrrev_i32_e32 v5, 31, v4
	v_readlane_b32 s19, v251, 20
	s_add_u32 s18, s49, s18
	v_mov_b32_e32 v121, v119
	v_lshl_or_b32 v128, v2, 3, v126
	v_lshlrev_b64 v[130:131], 11, v[4:5]
	v_bitop3_b32 v2, v4, v116, 15 bitop3:0x6c
	s_addc_u32 s19, s0, s19
	v_or_b32_e32 v118, v118, v7
	v_lshl_or_b32 v132, v2, 3, v130
	v_lshlrev_b32_e32 v2, 2, v4
	v_lshl_add_u64 v[4:5], v[120:121], 1, s[18:19]
	s_mov_b32 s5, m0
	s_mov_b32 m0, s23
	s_nop 0
	global_load_lds_dwordx4 v[4:5], off
	s_mov_b32 m0, s5
	v_lshl_add_u64 v[4:5], v[118:119], 1, s[18:19]
	v_mov_b32_e32 v125, v123
	v_lshl_add_u64 v[4:5], v[4:5], 0, s[2:3]
	s_mov_b32 s5, m0
	s_mov_b32 m0, s10
	s_nop 0
	global_load_lds_dwordx4 v[4:5], off
	s_mov_b32 m0, s5
	v_lshl_add_u64 v[4:5], v[124:125], 1, s[18:19]
	s_add_i32 s5, s23, 0x400
	s_mov_b32 s7, m0
	s_mov_b32 m0, s5
	s_nop 0
	global_load_lds_dwordx4 v[4:5], off
	s_mov_b32 m0, s7
	v_lshl_add_u64 v[4:5], v[122:123], 1, s[18:19]
	v_mov_b32_e32 v129, v127
	v_lshl_add_u64 v[4:5], v[4:5], 0, s[2:3]
	s_add_i32 s5, s10, 0x400
	v_or_b32_e32 v126, v126, v7
	s_mov_b32 s7, m0
	s_mov_b32 m0, s5
	s_nop 0
	global_load_lds_dwordx4 v[4:5], off
	s_mov_b32 m0, s7
	v_lshl_add_u64 v[4:5], v[128:129], 1, s[18:19]
	s_add_i32 s5, s23, 0x800
	v_bitop3_b32 v2, v2, v16, 12 bitop3:0x6c
	s_mov_b32 s7, m0
	s_mov_b32 m0, s5
	s_nop 0
	global_load_lds_dwordx4 v[4:5], off
	s_mov_b32 m0, s7
	v_lshl_add_u64 v[4:5], v[126:127], 1, s[18:19]
	s_add_i32 s5, s10, 0x800
	s_lshl_b32 s4, s4, 2
	v_mov_b32_e32 v133, v131
	v_or_b32_e32 v2, v2, v12
	v_lshl_add_u64 v[4:5], v[4:5], 0, s[2:3]
	s_mov_b32 s7, m0
	s_mov_b32 m0, s5
	s_nop 0
	global_load_lds_dwordx4 v[4:5], off
	s_mov_b32 m0, s7
	s_add_i32 s5, s23, 0xc00
	s_add_i32 s48, s4, 0
	v_lshl_or_b32 v130, v2, 3, v130
	v_lshl_add_u64 v[4:5], v[132:133], 1, s[18:19]
	s_mov_b32 s7, m0
	s_mov_b32 m0, s5
	s_nop 0
	global_load_lds_dwordx4 v[4:5], off
	s_mov_b32 m0, s7
	s_add_i32 s5, s10, 0xc00
	s_add_i32 s48, s48, 0x24800
	v_lshl_add_u64 v[4:5], v[130:131], 1, s[18:19]
	s_cmp_eq_u32 s6, 1
	v_lshl_add_u64 v[4:5], v[4:5], 0, s[2:3]
	s_mov_b32 s7, m0
	s_mov_b32 m0, s5
	s_nop 0
	global_load_lds_dwordx4 v[4:5], off
	s_mov_b32 m0, s7
	s_cselect_b64 s[4:5], -1, 0
	s_cmp_lg_u32 s6, 1
	v_readlane_b32 s18, v251, 17
	s_cselect_b64 s[6:7], -1, 0
	s_cmpk_gt_u32 s1, 0xff
	s_mov_b32 s29, s18
	v_readlane_b32 s18, v251, 14
	v_lshlrev_b32_e32 v154, 3, v11
	v_lshlrev_b32_e32 v134, 8, v11
	s_cselect_b64 s[20:21], -1, 0
	v_lshlrev_b32_e32 v155, 4, v11
	v_cmp_gt_u32_e64 s[38:39], 32, v10
	s_mov_b32 s76, 0
	v_cmp_eq_u32_e64 s[40:41], 0, v10
	v_lshl_or_b32 v156, v14, 6, v13
	v_lshl_or_b32 v157, v15, 6, v13
	s_mov_b32 s50, 0x10000
	v_readlane_b32 s1, v251, 12
	s_mov_b32 s28, s18
	v_readlane_b32 s19, v251, 18
	s_waitcnt vmcnt(0)
	s_branch .LBB0_537
